# up-GEMM epilogue-head ssq/bias loads prefetched at unit start into phase-free VGPRs; first K iteration peeled without its first two vmcnt waits
# speedup vs baseline: 1.0018x; 1.0018x over previous
; template <class Epi, int AMODE>
; __device__ __forceinline__ void gemm_phase(LAS unsigned char* lds, const Gemm g, const StaticOrder& S, const Epi& E, int stagger_us, int tid_in) {
;     ...
;     PG8_STAGE(PG8_SB(0, 0), cB, voffB); PG8_STAGE(PG8_SB(0, 1), cB + hstepB, voffB); PG8_STAGE(PG8_SA(0, 0), cA, voffA); PG8_STAGE(PG8_SA(0, 1), cA + hstepA, voffA);
;     if (wr == 1) PG8_BAR;
;     PG8_WAIT_V(2); PG8_BAR;
;     PG8_STAGE(PG8_SB(1, 0), cB + kstep, voffB); PG8_STAGE(PG8_SA(1, 0), cA + kstep, voffA); PG8_STAGE(PG8_SB(1, 1), cB + hstepB + kstep, voffB);
;     PG8_WAIT_V(6); PG8_BAR;
;     __device__ __forceinline__ void operator()(f32x4 (&acc)[2][2][4][2], const Unit& u, int wr, int wc, int fr, int fq) const {
;     ...
;         const int tok0 = 252 * u.pm + 126 * wr - 1;
;         {
;             const int tq = tok0 + 8 * fr; const int tA = tq < 0 ? 0 : (tq > TOK - 1 ? TOK - 1 : tq), tB = (tq + 7) > TOK - 1 ? TOK - 1 : (tq + 7);
;             const int bA = batch_of(tA), bB = batch_of(tB); const bool same = __all(bA == bB);
;             const float* bp0 = bias + 256 * u.pn + 32 * wc + 8 * fq;
;             f32x4 bvA[2][2]; float sq[8];
; #pragma unroll
;             for (int am = 0; am < 8; ++am) { int tok = tq + am; tok = tok < 0 ? 0 : (tok > TOK - 1 ? TOK - 1 : tok); sq[am] = LDG(float, ssq + tok); }
; #pragma unroll
;             for (int bj = 0; bj < 2; ++bj)
; #pragma unroll
;                 for (int n = 0; n < 2; ++n) bvA[bj][n] = LDG(f32x4, bp0 + (size_t)bA * (2 * DFF) + bj * HALF + 4 * n);
; #pragma unroll
;             for (int am = 0; am < 8; ++am) { const int ai = am >> 2, m = am & 3;
;                 const float rs = __builtin_amdgcn_rsqf(sq[am] * (1.f / DM) + EPS);
; #pragma unroll
;                 for (int bj = 0; bj < 2; ++bj)
; #pragma unroll
;                     for (int n = 0; n < 2; ++n) acc[ai][bj][m][n] = acc[ai][bj][m][n] * rs + bvA[bj][n];
;                 asm volatile("" : "+v"(acc[ai][0][m][0]), "+v"(acc[ai][0][m][1]), "+v"(acc[ai][1][m][0]), "+v"(acc[ai][1][m][1])); }
;             if (!same) {
;                 asm volatile("" ::: "memory");
;                 f32x4 dv[2][2];
; #pragma unroll
;                 for (int bj = 0; bj < 2; ++bj)
; #pragma unroll
;                     for (int n = 0; n < 2; ++n) dv[bj][n] = LDG(f32x4, bp0 + (size_t)bB * (2 * DFF) + bj * HALF + 4 * n) - bvA[bj][n];
; #pragma unroll
.LBB0_1287:
	s_mul_i32 s31, s69, 0x10200
	s_mul_hi_i32 s30, s69, 0x10200
	s_add_u32 s52, s40, s31
	s_addc_u32 s53, s41, s30
	s_mul_i32 s31, s69, 0x5600
	s_mul_hi_i32 s30, s69, 0x5600
	s_add_u32 s54, s38, s31
	s_addc_u32 s55, s39, s30
	s_lshl_b32 s30, s69, 1
	s_or_b32 s30, s30, 1
	s_mul_hi_i32 s31, s30, 0x28400
	s_mul_i32 s30, s30, 0x28400
	s_add_u32 s30, s6, s30
	s_addc_u32 s31, s7, s31
	s_add_u32 s56, s30, 0x100000
	s_addc_u32 s57, s31, 0
	s_mul_i32 s31, s69, 0xfa831000
	s_mul_hi_i32 s30, s69, 0xfa831000
	s_add_u32 s27, s27, s31
	s_addc_u32 s28, s28, s30
	s_ashr_i32 s66, s8, 31
	s_add_u32 s58, s52, 0x5600
	s_addc_u32 s59, s53, 0
	s_add_u32 s60, s52, 0xac00
	v_bfe_u32 v18, v10, 4, 2
	s_addc_u32 s61, s53, 0
	v_and_b32_e32 v17, 15, v10
	v_lshlrev_b32_e32 v19, 4, v18
	v_lshlrev_b32_e32 v21, 2, v10
	s_lshl_b32 s29, s29, 5
	v_lshl_or_b32 v20, v17, 6, v19
	s_lshl_b32 s30, s25, 13
	v_and_b32_e32 v21, 32, v21
	s_and_b32 s29, s29, 0x60
	v_bitop3_b32 v22, v20, s30, v21 bitop3:0xde
	s_lshl_b32 s30, s29, 7
	s_add_u32 s62, s6, 0x21400000
	s_addc_u32 s63, s7, 0
	s_add_i32 m0, s93, 0x18000
	v_lshl_add_u64 v[8:9], v[8:9], 0, s[74:75]
	s_waitcnt vmcnt(2)
	s_barrier
	global_load_lds_dwordx4 v[8:9], off
	v_lshl_add_u64 v[6:7], v[6:7], 0, s[74:75]
	s_add_i32 m0, s93, 0x1a000
	s_add_i32 s67, s93, 0x8000
	s_add_i32 s85, s93, 0xa000
	global_load_lds_dwordx4 v[6:7], off
	v_lshl_add_u64 v[2:3], v[2:3], 0, s[74:75]
	s_mov_b32 m0, s67
	s_add_u32 s6, s4, 0x80080
	global_load_lds_dwordx4 v[2:3], off
	v_lshl_add_u64 v[2:3], v[4:5], 0, s[74:75]
	s_mov_b32 m0, s85
	s_addc_u32 s7, s5, 0
	global_load_lds_dwordx4 v[2:3], off
	s_add_i32 m0, s93, 0x1c000
	v_lshl_add_u64 v[2:3], s[6:7], 0, v[0:1]
	global_load_lds_dwordx4 v[2:3], off
	v_lshl_add_u64 v[2:3], s[6:7], 0, v[182:183]
	s_add_i32 m0, s93, 0x1e000
	s_mulk_i32 s25, 0x7e
	global_load_lds_dwordx4 v[2:3], off
	v_lshlrev_b32_e32 v2, 3, v17
	v_add3_u32 v197, v2, s25, -1
	v_add_u32_e32 v2, -1, v10
	s_cmpk_lt_u32 s24, 0x100
	v_and_or_b32 v2, v2, 15, v19
	s_cselect_b64 s[48:49], -1, 0
	v_lshlrev_b32_e32 v198, 2, v2
	v_add_u32_e32 v2, 1, v10
	s_lshl_b32 s6, s29, 2
	v_and_or_b32 v2, v2, 15, v19
	s_add_u32 s6, s27, s6
	v_lshlrev_b32_e32 v199, 2, v2
	s_addc_u32 s7, s28, 0
	v_lshlrev_b32_e32 v2, 5, v18
	v_mov_b32_e32 v3, v1
	v_lshl_add_u64 v[2:3], s[6:7], 0, v[2:3]
	s_mov_b64 s[6:7], 0x930000
	v_lshl_add_u64 v[184:185], v[2:3], 0, s[6:7]
	v_and_b32_e32 v2, 1, v11
	v_lshlrev_b32_e32 v2, 6, v2
	v_lshlrev_b32_e32 v3, 1, v12
	v_add3_u32 v2, v13, v2, v3
	v_mov_b32_e32 v3, v1
	s_mov_b64 s[6:7], 0x4080
	v_lshl_add_u64 v[186:187], v[2:3], 0, s[6:7]
	v_and_b32_e32 v2, 1, v14
	s_waitcnt vmcnt(0)
	v_lshlrev_b32_e32 v2, 6, v2
	v_lshlrev_b32_e32 v3, 1, v15
	v_add3_u32 v2, v16, v2, v3
	v_mov_b32_e32 v3, v1
	v_bitop3_b32 v196, v20, s30, v21 bitop3:0xde
	s_mov_b32 s24, 0
	v_cmp_ne_u32_e64 s[36:37], 0, v17
	v_cmp_ne_u32_e64 s[38:39], 15, v17
	v_lshl_or_b32 v200, v18, 3, s29
	v_lshl_add_u64 v[188:189], v[2:3], 0, s[6:7]
	v_add_u32_e32 v201, 0, v22
	s_barrier
	s_branch .LBB0_1290

; #define PG8_STAGE(bufoff, gbase, voff) do { _Pragma("unroll") for (int _i = 0; _i < 2; ++_i) \
;         __builtin_amdgcn_global_load_lds((const unsigned*)((const char*)(gbase) + (voff)[_i]), (LAS unsigned*)(lds + (bufoff) + ldsw + _i * 8192), 16, 0, 0); } while (0)
; #define PG8_LDA(dst, b, h) do { _Pragma("unroll") for (int m = 0; m < 4; ++m) _Pragma("unroll") for (int k = 0; k < 2; ++k) dst[m][k] = *(const LAS bf16x8*)(lds + PG8_SA(b, h) + aoff + m * 2048 + k * 1024); } while (0)
; #define PG8_SCHED __builtin_amdgcn_sched_barrier(0)
; template <class Epi, int AMODE>
; __device__ __forceinline__ void gemm_phase(LAS unsigned char* lds, const Gemm g, const StaticOrder& S, const Epi& E, int stagger_us, int tid_in) {
;     ...
;         const bool has_next = S.next(ui + 1, nxt);
;         const char* nA = has_next ? Abase + (size_t)nxt.pm * tstepA : cA; const char* nB = has_next ? (const char*)g.Bt + (size_t)nxt.pn * tstepB : cB;
;         for (int t = 0; t < nt; t += 2) {
;             const bool last = (t == nt - 2);
;             const char* a1 = cA + (size_t)(t + 1) * kstep;
;             const char* a2 = last ? nA : cA + (size_t)(t + 2) * kstep; const char* b2 = last ? nB : cB + (size_t)(t + 2) * kstep;
;             const char* a3 = a2 + kstep; const char* b3 = b2 + kstep;
;             PG8_LDB(B0, 0, 0); PG8_LDB(B1, 0, 1); PG8_SCHED; PG8_LDA(At, 0, 0); PG8_STAGE(PG8_SA(1, 1), a1 + hstepA, voffA);
;     __device__ __forceinline__ void operator()(f32x4 (&acc)[2][2][4][2], const Unit& u, int wr, int wc, int fr, int fq) const {
;     ...
;             const int tq = tok0 + 8 * fr; const int tA = tq < 0 ? 0 : (tq > TOK - 1 ? TOK - 1 : tq), tB = (tq + 7) > TOK - 1 ? TOK - 1 : (tq + 7);
;             const int bA = batch_of(tA), bB = batch_of(tB); const bool same = __all(bA == bB);
;             const float* bp0 = bias + 256 * u.pn + 32 * wc + 8 * fq;
;             f32x4 bvA[2][2]; float sq[8];
; #pragma unroll
;             for (int am = 0; am < 8; ++am) { int tok = tq + am; tok = tok < 0 ? 0 : (tok > TOK - 1 ? TOK - 1 : tok); sq[am] = LDG(float, ssq + tok); }
; #pragma unroll
;             for (int bj = 0; bj < 2; ++bj)
; #pragma unroll
;                 for (int n = 0; n < 2; ++n) bvA[bj][n] = LDG(f32x4, bp0 + (size_t)bA * (2 * DFF) + bj * HALF + 4 * n);
.LBB0_1298:
	s_ashr_i32 s47, s46, 31
	s_lshl_b64 s[6:7], s[46:47], 20
	s_add_u32 s96, s9, s6
	s_addc_u32 s97, s72, s7
	s_and_b64 s[6:7], s[42:43], exec
	s_cselect_b32 s27, s97, s5
	s_cselect_b32 s28, s96, s4
	s_add_u32 s29, s4, 0x100
	v_mov_b32_e32 v2, 0
	s_addc_u32 s30, s5, 0
	s_mov_b32 s31, -2
	s_mul_i32 s6, s26, 0xfc
	v_add_u32_e32 v222, s6, v197
	v_med3_i32 v240, v222, 0, v238
	v_add_u32_e32 v241, 0xffffe000, v240
	v_lshrrev_b32_e32 v241, 12, v241
	v_add_u32_e32 v241, 4, v241
	v_lshrrev_b32_e32 v242, 11, v240
	v_mov_b32_e32 v243, 0x2000
	v_cmp_gt_i32_e64 s[6:7], v243, v222
	s_nop 1
	v_cndmask_b32_e64 v241, v241, v242, s[6:7]
	s_lshl_b32 s6, s92, 8
	s_ashr_i32 s7, s6, 31
	v_lshl_add_u64 v[236:237], s[6:7], 2, v[184:185]
	v_mad_u64_u32 v[236:237], s[6:7], v241, s15, v[236:237]
	v_med3_i32 v224, v222, 0, v238
	v_lshlrev_b32_e32 v224, 2, v224
	global_load_dword v224, v224, s[56:57]
	v_add_u32_e32 v228, 1, v222
	v_med3_i32 v228, v228, 0, v238
	v_lshlrev_b32_e32 v228, 2, v228
	global_load_dword v228, v228, s[56:57]
	v_add_u32_e32 v231, 2, v222
	v_med3_i32 v231, v231, 0, v238
	v_lshlrev_b32_e32 v231, 2, v231
	global_load_dword v231, v231, s[56:57]
	v_add_u32_e32 v233, 3, v222
	v_med3_i32 v233, v233, 0, v238
	v_lshlrev_b32_e32 v233, 2, v233
	global_load_dword v233, v233, s[56:57]
	v_add_u32_e32 v234, 4, v222
	v_med3_i32 v234, v234, 0, v238
	v_lshlrev_b32_e32 v234, 2, v234
	global_load_dword v234, v234, s[56:57]
	v_add_u32_e32 v239, 5, v222
	v_med3_i32 v239, v239, 0, v238
	v_lshlrev_b32_e32 v239, 2, v239
	global_load_dword v239, v239, s[56:57]
	v_add_u32_e32 v252, 6, v222
	v_med3_i32 v252, v252, 0, v238
	v_lshlrev_b32_e32 v252, 2, v252
	global_load_dword v252, v252, s[56:57]
	v_add_u32_e32 v253, 7, v222
	v_med3_i32 v253, v253, 0, v238
	v_lshlrev_b32_e32 v253, 2, v253
	global_load_dword v253, v253, s[56:57]
	global_load_dwordx4 v[240:243], v[236:237], off
	global_load_dwordx4 v[244:247], v[236:237], off offset:16
	global_load_dwordx4 v[248:251], v[236:237], off offset:512
	global_load_dwordx2 v[222:223], v[236:237], off offset:528
	s_nop 0
	global_load_dwordx2 v[236:237], v[236:237], off offset:536
	v_mov_b32_e32 v3, v2
	v_mov_b32_e32 v4, v2
	v_mov_b32_e32 v5, v2
	v_mov_b32_e32 v14, v2
	v_mov_b32_e32 v15, v2
	v_mov_b32_e32 v16, v2
	v_mov_b32_e32 v17, v2
	v_mov_b32_e32 v10, v2
	v_mov_b32_e32 v11, v2
	v_mov_b32_e32 v12, v2
	v_mov_b32_e32 v13, v2
	v_mov_b32_e32 v26, v2
	v_mov_b32_e32 v27, v2
	v_mov_b32_e32 v28, v2
	v_mov_b32_e32 v29, v2
	v_mov_b32_e32 v6, v2
	v_mov_b32_e32 v7, v2
	v_mov_b32_e32 v8, v2
	v_mov_b32_e32 v9, v2
	v_mov_b32_e32 v42, v2
	v_mov_b32_e32 v43, v2
	v_mov_b32_e32 v44, v2
	v_mov_b32_e32 v45, v2
	v_mov_b32_e32 v30, v2
	v_mov_b32_e32 v31, v2
	v_mov_b32_e32 v32, v2
	v_mov_b32_e32 v33, v2
	v_mov_b32_e32 v58, v2
	v_mov_b32_e32 v59, v2
	v_mov_b32_e32 v60, v2
	v_mov_b32_e32 v61, v2
	v_mov_b32_e32 v74, v2
	v_mov_b32_e32 v75, v2
	v_mov_b32_e32 v76, v2
	v_mov_b32_e32 v77, v2
	v_mov_b32_e32 v22, v2
	v_mov_b32_e32 v23, v2
	v_mov_b32_e32 v24, v2
	v_mov_b32_e32 v25, v2
	v_mov_b32_e32 v34, v2
	v_mov_b32_e32 v35, v2
	v_mov_b32_e32 v36, v2
	v_mov_b32_e32 v37, v2
	v_mov_b32_e32 v18, v2
	v_mov_b32_e32 v19, v2
	v_mov_b32_e32 v20, v2
	v_mov_b32_e32 v21, v2
	v_mov_b32_e32 v50, v2
	v_mov_b32_e32 v51, v2
	v_mov_b32_e32 v52, v2
	v_mov_b32_e32 v53, v2
	v_mov_b32_e32 v38, v2
	v_mov_b32_e32 v39, v2
	v_mov_b32_e32 v40, v2
	v_mov_b32_e32 v41, v2
	v_mov_b32_e32 v46, v2
	v_mov_b32_e32 v47, v2
	v_mov_b32_e32 v48, v2
	v_mov_b32_e32 v49, v2
	v_mov_b32_e32 v54, v2
	v_mov_b32_e32 v55, v2
	v_mov_b32_e32 v56, v2
	v_mov_b32_e32 v57, v2
	v_mov_b32_e32 v66, v2
	v_mov_b32_e32 v67, v2
	v_mov_b32_e32 v68, v2
	v_mov_b32_e32 v69, v2
	v_mov_b32_e32 v78, v2
	v_mov_b32_e32 v79, v2
	v_mov_b32_e32 v80, v2
	v_mov_b32_e32 v81, v2
	v_mov_b32_e32 v62, v2
	v_mov_b32_e32 v63, v2
	v_mov_b32_e32 v64, v2
	v_mov_b32_e32 v65, v2
	v_mov_b32_e32 v70, v2
	v_mov_b32_e32 v71, v2
	v_mov_b32_e32 v72, v2
	v_mov_b32_e32 v73, v2
	v_mov_b32_e32 v86, v2
	v_mov_b32_e32 v87, v2
	v_mov_b32_e32 v88, v2
	v_mov_b32_e32 v89, v2
	v_mov_b32_e32 v94, v2
	v_mov_b32_e32 v95, v2
	v_mov_b32_e32 v96, v2
	v_mov_b32_e32 v97, v2
	v_mov_b32_e32 v98, v2
	v_mov_b32_e32 v99, v2
	v_mov_b32_e32 v100, v2
	v_mov_b32_e32 v101, v2
	v_mov_b32_e32 v106, v2
	v_mov_b32_e32 v107, v2
	v_mov_b32_e32 v108, v2
	v_mov_b32_e32 v109, v2
	v_mov_b32_e32 v82, v2
	v_mov_b32_e32 v83, v2
	v_mov_b32_e32 v84, v2
	v_mov_b32_e32 v85, v2
	v_mov_b32_e32 v90, v2
	v_mov_b32_e32 v91, v2
	v_mov_b32_e32 v92, v2
	v_mov_b32_e32 v93, v2
	v_mov_b32_e32 v102, v2
	v_mov_b32_e32 v103, v2
	v_mov_b32_e32 v104, v2
	v_mov_b32_e32 v105, v2
	v_mov_b32_e32 v110, v2
	v_mov_b32_e32 v111, v2
	v_mov_b32_e32 v112, v2
	v_mov_b32_e32 v113, v2
	v_mov_b32_e32 v114, v2
	v_mov_b32_e32 v115, v2
	v_mov_b32_e32 v116, v2
	v_mov_b32_e32 v117, v2
	v_mov_b32_e32 v118, v2
	v_mov_b32_e32 v119, v2
	v_mov_b32_e32 v120, v2
	v_mov_b32_e32 v121, v2
	v_mov_b32_e32 v122, v2
	v_mov_b32_e32 v123, v2
	v_mov_b32_e32 v124, v2
	v_mov_b32_e32 v125, v2
	v_mov_b32_e32 v126, v2
	v_mov_b32_e32 v127, v2
	v_mov_b32_e32 v128, v2
	v_mov_b32_e32 v129, v2
	s_add_u32 s4, s44, 0x100
	s_addc_u32 s5, s45, 0
	s_add_i32 s34, 0, 0x10000
	s_cmp_eq_u32 s31, 28
	s_cselect_b32 s43, s95, s5
	s_cselect_b32 s42, s94, s4
	s_cselect_b32 s7, s27, s30
	s_cselect_b32 s6, s28, s29
	s_add_i32 s35, 0, 0x14000
	v_add_u32_e32 v142, s34, v196
	v_add_u32_e32 v158, s35, v196
	ds_read_b128 v[130:133], v142
	ds_read_b128 v[134:137], v142 offset:1024
	ds_read_b128 v[138:141], v142 offset:2048
	ds_read_b128 v[142:145], v142 offset:3072
	ds_read_b128 v[146:149], v158
	ds_read_b128 v[150:153], v158 offset:1024
	ds_read_b128 v[154:157], v158 offset:2048
	ds_read_b128 v[158:161], v158 offset:3072
	v_lshl_add_u64 v[194:195], s[44:45], 0, v[186:187]
	s_add_i32 m0, s93, 0xc000
	ds_read_b128 v[162:165], v201
	ds_read_b128 v[166:169], v201 offset:1024
	ds_read_b128 v[170:173], v201 offset:2048
	ds_read_b128 v[174:177], v201 offset:3072
	ds_read_b128 v[190:193], v201 offset:4096
	ds_read_b128 v[202:205], v201 offset:5120
	ds_read_b128 v[206:209], v201 offset:6144
	ds_read_b128 v[210:213], v201 offset:7168
	global_load_lds_dwordx4 v[194:195], off
	v_lshl_add_u64 v[194:195], s[44:45], 0, v[188:189]
	s_add_i32 m0, s93, 0xe000
	s_nop 0
	global_load_lds_dwordx4 v[194:195], off
	s_waitcnt lgkmcnt(0)
	s_barrier
; #define PG8_STAGE(bufoff, gbase, voff) do { _Pragma("unroll") for (int _i = 0; _i < 2; ++_i) \
;         __builtin_amdgcn_global_load_lds((const unsigned*)((const char*)(gbase) + (voff)[_i]), (LAS unsigned*)(lds + (bufoff) + ldsw + _i * 8192), 16, 0, 0); } while (0)
; #define PG8_LDA(dst, b, h) do { _Pragma("unroll") for (int m = 0; m < 4; ++m) _Pragma("unroll") for (int k = 0; k < 2; ++k) dst[m][k] = *(const LAS bf16x8*)(lds + PG8_SA(b, h) + aoff + m * 2048 + k * 1024); } while (0)
; #define PG8_LDB(dst, b, h) do { _Pragma("unroll") for (int n = 0; n < 2; ++n) _Pragma("unroll") for (int k = 0; k < 2; ++k) dst[n][k] = *(const LAS bf16x8*)(lds + PG8_SB(b, h) + boff + n * 2048 + k * 1024); } while (0)
; #define PG8_MMA(ai, bj, At, Bt) do { __builtin_amdgcn_s_setprio(1); _Pragma("unroll") for (int m = 0; m < 4; ++m) _Pragma("unroll") for (int n = 0; n < 2; ++n) _Pragma("unroll") for (int k = 0; k < 2; ++k) \
;         acc[ai][bj][m][n] = __builtin_amdgcn_mfma_f32_16x16x32_bf16(Bt[n][k], At[m][k], acc[ai][bj][m][n], 0, 0, 0); __builtin_amdgcn_s_setprio(0); } while (0)
; #define PG8_WAIT_V(n) asm volatile("s_waitcnt vmcnt(" #n ")" ::: "memory")
; #define PG8_WAIT_L(n) asm volatile("s_waitcnt lgkmcnt(" #n ")" ::: "memory")
; #define PG8_BAR __builtin_amdgcn_s_barrier()
; #define PG8_SCHED __builtin_amdgcn_sched_barrier(0)
; template <class Epi, int AMODE>
; __device__ __forceinline__ void gemm_phase(LAS unsigned char* lds, const Gemm g, const StaticOrder& S, const Epi& E, int stagger_us, int tid_in) {
;     ...
;             PG8_LDB(B0, 0, 0); PG8_LDB(B1, 0, 1); PG8_SCHED; PG8_LDA(At, 0, 0); PG8_STAGE(PG8_SA(1, 1), a1 + hstepA, voffA);
;             PG8_WAIT_V(8); PG8_WAIT_L(0); PG8_BAR; PG8_MMA(0, 0, At, B0); PG8_MMA(0, 1, At, B1); PG8_BAR; PG8_SCHED;
;             PG8_LDA(At, 0, 1); PG8_STAGE(PG8_SB(0, 0), b2, voffB); PG8_STAGE(PG8_SB(0, 1), b2 + hstepB, voffB); PG8_STAGE(PG8_SA(0, 0), a2, voffA);
;             PG8_WAIT_V(8); PG8_WAIT_L(0); PG8_BAR; PG8_MMA(1, 0, At, B0); PG8_MMA(1, 1, At, B1); PG8_BAR; PG8_SCHED;
	s_setprio 1
	s_waitcnt lgkmcnt(0)
	v_mfma_f32_16x16x32_bf16 v[126:129], v[130:133], v[162:165], v[126:129]
	v_mfma_f32_16x16x32_bf16 v[122:125], v[138:141], v[162:165], v[122:125]
	v_mfma_f32_16x16x32_bf16 v[118:121], v[130:133], v[170:173], v[118:121]
	v_mfma_f32_16x16x32_bf16 v[114:117], v[138:141], v[170:173], v[114:117]
	v_mfma_f32_16x16x32_bf16 v[110:113], v[130:133], v[190:193], v[110:113]
	v_mfma_f32_16x16x32_bf16 v[102:105], v[138:141], v[190:193], v[102:105]
	v_mfma_f32_16x16x32_bf16 v[90:93], v[130:133], v[206:209], v[90:93]
	v_mfma_f32_16x16x32_bf16 v[82:85], v[138:141], v[206:209], v[82:85]
	v_mfma_f32_16x16x32_bf16 v[126:129], v[134:137], v[166:169], v[126:129]
	v_mfma_f32_16x16x32_bf16 v[122:125], v[142:145], v[166:169], v[122:125]
	v_mfma_f32_16x16x32_bf16 v[118:121], v[134:137], v[174:177], v[118:121]
	v_mfma_f32_16x16x32_bf16 v[114:117], v[142:145], v[174:177], v[114:117]
	v_mfma_f32_16x16x32_bf16 v[110:113], v[134:137], v[202:205], v[110:113]
	v_mfma_f32_16x16x32_bf16 v[102:105], v[142:145], v[202:205], v[102:105]
	v_mfma_f32_16x16x32_bf16 v[90:93], v[134:137], v[210:213], v[90:93]
	v_mfma_f32_16x16x32_bf16 v[82:85], v[142:145], v[210:213], v[82:85]
	s_setprio 0
	s_setprio 1
	v_mfma_f32_16x16x32_bf16 v[106:109], v[146:149], v[162:165], v[106:109]
	v_mfma_f32_16x16x32_bf16 v[98:101], v[154:157], v[162:165], v[98:101]
	v_mfma_f32_16x16x32_bf16 v[94:97], v[146:149], v[170:173], v[94:97]
	v_mfma_f32_16x16x32_bf16 v[86:89], v[154:157], v[170:173], v[86:89]
	v_mfma_f32_16x16x32_bf16 v[70:73], v[146:149], v[190:193], v[70:73]
	v_mfma_f32_16x16x32_bf16 v[62:65], v[154:157], v[190:193], v[62:65]
	v_mfma_f32_16x16x32_bf16 v[78:81], v[146:149], v[206:209], v[78:81]
	v_mfma_f32_16x16x32_bf16 v[66:69], v[154:157], v[206:209], v[66:69]
	v_mfma_f32_16x16x32_bf16 v[106:109], v[150:153], v[166:169], v[106:109]
	v_mfma_f32_16x16x32_bf16 v[98:101], v[158:161], v[166:169], v[98:101]
	v_mfma_f32_16x16x32_bf16 v[94:97], v[150:153], v[174:177], v[94:97]
	v_mfma_f32_16x16x32_bf16 v[86:89], v[158:161], v[174:177], v[86:89]
	v_mfma_f32_16x16x32_bf16 v[70:73], v[150:153], v[202:205], v[70:73]
	v_mfma_f32_16x16x32_bf16 v[62:65], v[158:161], v[202:205], v[62:65]
	v_mfma_f32_16x16x32_bf16 v[78:81], v[150:153], v[210:213], v[78:81]
	v_mfma_f32_16x16x32_bf16 v[66:69], v[158:161], v[210:213], v[66:69]
	s_setprio 0
	s_barrier
	s_add_i32 s34, s34, s91
	v_lshl_add_u64 v[194:195], s[6:7], 0, v[0:1]
	s_mov_b32 m0, s34
	ds_read_b128 v[162:165], v201 offset:16384
	ds_read_b128 v[166:169], v201 offset:17408
	ds_read_b128 v[170:173], v201 offset:18432
	ds_read_b128 v[174:177], v201 offset:19456
	ds_read_b128 v[190:193], v201 offset:20480
	ds_read_b128 v[202:205], v201 offset:21504
	ds_read_b128 v[206:209], v201 offset:22528
	ds_read_b128 v[210:213], v201 offset:23552
	global_load_lds_dwordx4 v[194:195], off
	s_add_i32 m0, s34, 0x2000
	s_add_u32 s44, s6, 0x80000
	v_lshl_add_u64 v[214:215], s[6:7], 0, v[182:183]
	s_addc_u32 s45, s7, 0
	s_add_i32 s34, s35, s91
	global_load_lds_dwordx4 v[214:215], off
	v_lshl_add_u64 v[216:217], s[44:45], 0, v[0:1]
	s_mov_b32 m0, s34
	v_lshl_add_u64 v[218:219], s[42:43], 0, v[180:181]
	global_load_lds_dwordx4 v[216:217], off
	v_lshl_add_u64 v[216:217], s[44:45], 0, v[182:183]
	s_add_i32 m0, s34, 0x2000
	s_nop 0
	global_load_lds_dwordx4 v[216:217], off
	v_lshl_add_u64 v[216:217], s[42:43], 0, v[178:179]
	s_mov_b32 m0, s93
	s_nop 0
	global_load_lds_dwordx4 v[216:217], off
	s_mov_b32 m0, s83
	s_nop 0
	global_load_lds_dwordx4 v[218:219], off
	s_waitcnt lgkmcnt(0)
	s_barrier
	s_setprio 1
	s_waitcnt lgkmcnt(0)
	v_mfma_f32_16x16x32_bf16 v[54:57], v[130:133], v[162:165], v[54:57]
	v_mfma_f32_16x16x32_bf16 v[46:49], v[138:141], v[162:165], v[46:49]
	v_mfma_f32_16x16x32_bf16 v[38:41], v[130:133], v[170:173], v[38:41]
	v_mfma_f32_16x16x32_bf16 v[50:53], v[138:141], v[170:173], v[50:53]
	v_mfma_f32_16x16x32_bf16 v[18:21], v[130:133], v[190:193], v[18:21]
	v_mfma_f32_16x16x32_bf16 v[34:37], v[138:141], v[190:193], v[34:37]
	v_mfma_f32_16x16x32_bf16 v[22:25], v[130:133], v[206:209], v[22:25]
	v_mfma_f32_16x16x32_bf16 v[74:77], v[138:141], v[206:209], v[74:77]
	v_mfma_f32_16x16x32_bf16 v[54:57], v[134:137], v[166:169], v[54:57]
	v_mfma_f32_16x16x32_bf16 v[46:49], v[142:145], v[166:169], v[46:49]
	v_mfma_f32_16x16x32_bf16 v[38:41], v[134:137], v[174:177], v[38:41]
	v_mfma_f32_16x16x32_bf16 v[50:53], v[142:145], v[174:177], v[50:53]
	v_mfma_f32_16x16x32_bf16 v[18:21], v[134:137], v[202:205], v[18:21]
	v_mfma_f32_16x16x32_bf16 v[34:37], v[142:145], v[202:205], v[34:37]
	v_mfma_f32_16x16x32_bf16 v[22:25], v[134:137], v[210:213], v[22:25]
	v_mfma_f32_16x16x32_bf16 v[74:77], v[142:145], v[210:213], v[74:77]
	s_setprio 0
	s_setprio 1
	v_mfma_f32_16x16x32_bf16 v[58:61], v[146:149], v[162:165], v[58:61]
	v_mfma_f32_16x16x32_bf16 v[30:33], v[154:157], v[162:165], v[30:33]
	v_mfma_f32_16x16x32_bf16 v[42:45], v[146:149], v[170:173], v[42:45]
	v_mfma_f32_16x16x32_bf16 v[6:9], v[154:157], v[170:173], v[6:9]
	v_mfma_f32_16x16x32_bf16 v[26:29], v[146:149], v[190:193], v[26:29]
	v_mfma_f32_16x16x32_bf16 v[10:13], v[154:157], v[190:193], v[10:13]
	v_mfma_f32_16x16x32_bf16 v[14:17], v[146:149], v[206:209], v[14:17]
	v_mfma_f32_16x16x32_bf16 v[2:5], v[154:157], v[206:209], v[2:5]
	v_mfma_f32_16x16x32_bf16 v[58:61], v[150:153], v[166:169], v[58:61]
	v_mfma_f32_16x16x32_bf16 v[30:33], v[158:161], v[166:169], v[30:33]
	v_mfma_f32_16x16x32_bf16 v[42:45], v[150:153], v[174:177], v[42:45]
	v_mfma_f32_16x16x32_bf16 v[6:9], v[158:161], v[174:177], v[6:9]
	v_mfma_f32_16x16x32_bf16 v[26:29], v[150:153], v[202:205], v[26:29]
	v_mfma_f32_16x16x32_bf16 v[10:13], v[158:161], v[202:205], v[10:13]
	v_mfma_f32_16x16x32_bf16 v[14:17], v[150:153], v[210:213], v[14:17]
	v_mfma_f32_16x16x32_bf16 v[2:5], v[158:161], v[210:213], v[2:5]
	s_setprio 0
	s_barrier
; #define PG8_STAGE(bufoff, gbase, voff) do { _Pragma("unroll") for (int _i = 0; _i < 2; ++_i) \
;         __builtin_amdgcn_global_load_lds((const unsigned*)((const char*)(gbase) + (voff)[_i]), (LAS unsigned*)(lds + (bufoff) + ldsw + _i * 8192), 16, 0, 0); } while (0)
; #define PG8_LDA(dst, b, h) do { _Pragma("unroll") for (int m = 0; m < 4; ++m) _Pragma("unroll") for (int k = 0; k < 2; ++k) dst[m][k] = *(const LAS bf16x8*)(lds + PG8_SA(b, h) + aoff + m * 2048 + k * 1024); } while (0)
; #define PG8_LDB(dst, b, h) do { _Pragma("unroll") for (int n = 0; n < 2; ++n) _Pragma("unroll") for (int k = 0; k < 2; ++k) dst[n][k] = *(const LAS bf16x8*)(lds + PG8_SB(b, h) + boff + n * 2048 + k * 1024); } while (0)
; #define PG8_MMA(ai, bj, At, Bt) do { __builtin_amdgcn_s_setprio(1); _Pragma("unroll") for (int m = 0; m < 4; ++m) _Pragma("unroll") for (int n = 0; n < 2; ++n) _Pragma("unroll") for (int k = 0; k < 2; ++k) \
;         acc[ai][bj][m][n] = __builtin_amdgcn_mfma_f32_16x16x32_bf16(Bt[n][k], At[m][k], acc[ai][bj][m][n], 0, 0, 0); __builtin_amdgcn_s_setprio(0); } while (0)
; #define PG8_WAIT_V(n) asm volatile("s_waitcnt vmcnt(" #n ")" ::: "memory")
; #define PG8_WAIT_L(n) asm volatile("s_waitcnt lgkmcnt(" #n ")" ::: "memory")
; #define PG8_BAR __builtin_amdgcn_s_barrier()
; #define PG8_SCHED __builtin_amdgcn_sched_barrier(0)
; template <class Epi, int AMODE>
; __device__ __forceinline__ void gemm_phase(LAS unsigned char* lds, const Gemm g, const StaticOrder& S, const Epi& E, int stagger_us, int tid_in) {
;     ...
;             PG8_LDB(B0, 1, 0); PG8_LDB(B1, 1, 1); PG8_SCHED; PG8_LDA(At, 1, 0); PG8_STAGE(PG8_SA(0, 1), a2 + hstepA, voffA);
;             PG8_WAIT_V(8); PG8_WAIT_L(0); PG8_BAR; PG8_MMA(0, 0, At, B0); PG8_MMA(0, 1, At, B1); PG8_BAR; PG8_SCHED;
	s_add_i32 s34, 0, 0x18000
	s_add_i32 s35, 0, 0x1c000
	v_add_u32_e32 v142, s34, v196
	v_add_u32_e32 v158, s35, v196
	ds_read_b128 v[130:133], v142
	ds_read_b128 v[134:137], v142 offset:1024
	ds_read_b128 v[138:141], v142 offset:2048
	ds_read_b128 v[142:145], v142 offset:3072
	ds_read_b128 v[146:149], v158
	ds_read_b128 v[150:153], v158 offset:1024
	ds_read_b128 v[154:157], v158 offset:2048
	ds_read_b128 v[158:161], v158 offset:3072
	s_add_u32 s42, s42, 0x4000
	s_addc_u32 s43, s43, 0
	s_mov_b32 m0, s79
	v_lshl_add_u64 v[220:221], s[42:43], 0, v[178:179]
	ds_read_b128 v[162:165], v201 offset:32768
	ds_read_b128 v[166:169], v201 offset:33792
	ds_read_b128 v[170:173], v201 offset:34816
	ds_read_b128 v[174:177], v201 offset:35840
	ds_read_b128 v[190:193], v201 offset:36864
	ds_read_b128 v[202:205], v201 offset:37888
	ds_read_b128 v[206:209], v201 offset:38912
	ds_read_b128 v[210:213], v201 offset:39936
	global_load_lds_dwordx4 v[220:221], off
	v_lshl_add_u64 v[220:221], s[42:43], 0, v[180:181]
	s_mov_b32 m0, s87
	s_nop 0
	global_load_lds_dwordx4 v[220:221], off
	s_waitcnt vmcnt(8)
	s_waitcnt lgkmcnt(0)
	s_barrier
	s_setprio 1
	s_waitcnt lgkmcnt(0)
	v_mfma_f32_16x16x32_bf16 v[126:129], v[130:133], v[162:165], v[126:129]
	v_mfma_f32_16x16x32_bf16 v[122:125], v[138:141], v[162:165], v[122:125]
	v_mfma_f32_16x16x32_bf16 v[118:121], v[130:133], v[170:173], v[118:121]
	v_mfma_f32_16x16x32_bf16 v[114:117], v[138:141], v[170:173], v[114:117]
	v_mfma_f32_16x16x32_bf16 v[110:113], v[130:133], v[190:193], v[110:113]
	v_mfma_f32_16x16x32_bf16 v[102:105], v[138:141], v[190:193], v[102:105]
	v_mfma_f32_16x16x32_bf16 v[90:93], v[130:133], v[206:209], v[90:93]
	v_mfma_f32_16x16x32_bf16 v[82:85], v[138:141], v[206:209], v[82:85]
	v_mfma_f32_16x16x32_bf16 v[126:129], v[134:137], v[166:169], v[126:129]
	v_mfma_f32_16x16x32_bf16 v[122:125], v[142:145], v[166:169], v[122:125]
	v_mfma_f32_16x16x32_bf16 v[118:121], v[134:137], v[174:177], v[118:121]
	v_mfma_f32_16x16x32_bf16 v[114:117], v[142:145], v[174:177], v[114:117]
	v_mfma_f32_16x16x32_bf16 v[110:113], v[134:137], v[202:205], v[110:113]
	v_mfma_f32_16x16x32_bf16 v[102:105], v[142:145], v[202:205], v[102:105]
	v_mfma_f32_16x16x32_bf16 v[90:93], v[134:137], v[210:213], v[90:93]
	v_mfma_f32_16x16x32_bf16 v[82:85], v[142:145], v[210:213], v[82:85]
	s_setprio 0
	s_setprio 1
	v_mfma_f32_16x16x32_bf16 v[106:109], v[146:149], v[162:165], v[106:109]
	v_mfma_f32_16x16x32_bf16 v[98:101], v[154:157], v[162:165], v[98:101]
	v_mfma_f32_16x16x32_bf16 v[94:97], v[146:149], v[170:173], v[94:97]
	v_mfma_f32_16x16x32_bf16 v[86:89], v[154:157], v[170:173], v[86:89]
	v_mfma_f32_16x16x32_bf16 v[70:73], v[146:149], v[190:193], v[70:73]
	v_mfma_f32_16x16x32_bf16 v[62:65], v[154:157], v[190:193], v[62:65]
	v_mfma_f32_16x16x32_bf16 v[78:81], v[146:149], v[206:209], v[78:81]
	v_mfma_f32_16x16x32_bf16 v[66:69], v[154:157], v[206:209], v[66:69]
	v_mfma_f32_16x16x32_bf16 v[106:109], v[150:153], v[166:169], v[106:109]
	v_mfma_f32_16x16x32_bf16 v[98:101], v[158:161], v[166:169], v[98:101]
	v_mfma_f32_16x16x32_bf16 v[94:97], v[150:153], v[174:177], v[94:97]
	v_mfma_f32_16x16x32_bf16 v[86:89], v[158:161], v[174:177], v[86:89]
	v_mfma_f32_16x16x32_bf16 v[70:73], v[150:153], v[202:205], v[70:73]
	v_mfma_f32_16x16x32_bf16 v[62:65], v[158:161], v[202:205], v[62:65]
	v_mfma_f32_16x16x32_bf16 v[78:81], v[150:153], v[210:213], v[78:81]
	v_mfma_f32_16x16x32_bf16 v[66:69], v[158:161], v[210:213], v[66:69]
	s_setprio 0
	s_barrier
; #define PG8_STAGE(bufoff, gbase, voff) do { _Pragma("unroll") for (int _i = 0; _i < 2; ++_i) \
;         __builtin_amdgcn_global_load_lds((const unsigned*)((const char*)(gbase) + (voff)[_i]), (LAS unsigned*)(lds + (bufoff) + ldsw + _i * 8192), 16, 0, 0); } while (0)
; #define PG8_LDA(dst, b, h) do { _Pragma("unroll") for (int m = 0; m < 4; ++m) _Pragma("unroll") for (int k = 0; k < 2; ++k) dst[m][k] = *(const LAS bf16x8*)(lds + PG8_SA(b, h) + aoff + m * 2048 + k * 1024); } while (0)
; #define PG8_MMA(ai, bj, At, Bt) do { __builtin_amdgcn_s_setprio(1); _Pragma("unroll") for (int m = 0; m < 4; ++m) _Pragma("unroll") for (int n = 0; n < 2; ++n) _Pragma("unroll") for (int k = 0; k < 2; ++k) \
;         acc[ai][bj][m][n] = __builtin_amdgcn_mfma_f32_16x16x32_bf16(Bt[n][k], At[m][k], acc[ai][bj][m][n], 0, 0, 0); __builtin_amdgcn_s_setprio(0); } while (0)
; #define PG8_WAIT_V(n) asm volatile("s_waitcnt vmcnt(" #n ")" ::: "memory")
; #define PG8_WAIT_L(n) asm volatile("s_waitcnt lgkmcnt(" #n ")" ::: "memory")
; #define PG8_BAR __builtin_amdgcn_s_barrier()
; #define PG8_SCHED __builtin_amdgcn_sched_barrier(0)
; template <class Epi, int AMODE>
; __device__ __forceinline__ void gemm_phase(LAS unsigned char* lds, const Gemm g, const StaticOrder& S, const Epi& E, int stagger_us, int tid_in) {
;     ...
;             PG8_LDA(At, 1, 1); PG8_STAGE(PG8_SB(1, 0), b3, voffB); PG8_STAGE(PG8_SB(1, 1), b3 + hstepB, voffB); PG8_STAGE(PG8_SA(1, 0), a3, voffA);
;             PG8_WAIT_V(8); PG8_WAIT_L(0); PG8_BAR; PG8_MMA(1, 0, At, B0); PG8_MMA(1, 1, At, B1); PG8_BAR; PG8_SCHED;
;         }
	s_add_i32 s34, s34, s91
	v_lshl_add_u64 v[194:195], v[194:195], 0, s[74:75]
	s_mov_b32 m0, s34
	ds_read_b128 v[162:165], v201 offset:49152
	ds_read_b128 v[166:169], v201 offset:50176
	ds_read_b128 v[170:173], v201 offset:51200
	ds_read_b128 v[174:177], v201 offset:52224
	ds_read_b128 v[190:193], v201 offset:53248
	ds_read_b128 v[202:205], v201 offset:54272
	ds_read_b128 v[206:209], v201 offset:55296
	ds_read_b128 v[210:213], v201 offset:56320
	global_load_lds_dwordx4 v[194:195], off
	s_add_i32 m0, s34, 0x2000
	s_add_u32 s6, s6, 0x80080
	v_lshl_add_u64 v[194:195], v[214:215], 0, s[74:75]
	s_addc_u32 s7, s7, 0
	s_add_i32 s34, s35, s91
	global_load_lds_dwordx4 v[194:195], off
	v_lshl_add_u64 v[194:195], s[6:7], 0, v[0:1]
	s_mov_b32 m0, s34
	s_nop 0
	global_load_lds_dwordx4 v[194:195], off
	v_lshl_add_u64 v[194:195], s[6:7], 0, v[182:183]
	s_add_i32 m0, s34, 0x2000
	s_nop 0
	global_load_lds_dwordx4 v[194:195], off
	v_lshl_add_u64 v[194:195], v[216:217], 0, s[74:75]
	s_mov_b32 m0, s67
	s_nop 0
	global_load_lds_dwordx4 v[194:195], off
	v_lshl_add_u64 v[194:195], v[218:219], 0, s[74:75]
	s_mov_b32 m0, s85
	s_nop 0
	global_load_lds_dwordx4 v[194:195], off
	s_waitcnt vmcnt(8)
	s_waitcnt lgkmcnt(0)
	s_barrier
	s_setprio 1
	s_waitcnt lgkmcnt(0)
	v_mfma_f32_16x16x32_bf16 v[54:57], v[130:133], v[162:165], v[54:57]
	v_mfma_f32_16x16x32_bf16 v[46:49], v[138:141], v[162:165], v[46:49]
	v_mfma_f32_16x16x32_bf16 v[38:41], v[130:133], v[170:173], v[38:41]
	v_mfma_f32_16x16x32_bf16 v[50:53], v[138:141], v[170:173], v[50:53]
	v_mfma_f32_16x16x32_bf16 v[18:21], v[130:133], v[190:193], v[18:21]
	v_mfma_f32_16x16x32_bf16 v[34:37], v[138:141], v[190:193], v[34:37]
	v_mfma_f32_16x16x32_bf16 v[22:25], v[130:133], v[206:209], v[22:25]
	v_mfma_f32_16x16x32_bf16 v[74:77], v[138:141], v[206:209], v[74:77]
	v_mfma_f32_16x16x32_bf16 v[54:57], v[134:137], v[166:169], v[54:57]
	v_mfma_f32_16x16x32_bf16 v[46:49], v[142:145], v[166:169], v[46:49]
	v_mfma_f32_16x16x32_bf16 v[38:41], v[134:137], v[174:177], v[38:41]
	v_mfma_f32_16x16x32_bf16 v[50:53], v[142:145], v[174:177], v[50:53]
	v_mfma_f32_16x16x32_bf16 v[18:21], v[134:137], v[202:205], v[18:21]
	v_mfma_f32_16x16x32_bf16 v[34:37], v[142:145], v[202:205], v[34:37]
	v_mfma_f32_16x16x32_bf16 v[22:25], v[134:137], v[210:213], v[22:25]
	v_mfma_f32_16x16x32_bf16 v[74:77], v[142:145], v[210:213], v[74:77]
	s_setprio 0
	s_setprio 1
	v_mfma_f32_16x16x32_bf16 v[58:61], v[146:149], v[162:165], v[58:61]
	v_mfma_f32_16x16x32_bf16 v[30:33], v[154:157], v[162:165], v[30:33]
	v_mfma_f32_16x16x32_bf16 v[42:45], v[146:149], v[170:173], v[42:45]
	v_mfma_f32_16x16x32_bf16 v[6:9], v[154:157], v[170:173], v[6:9]
	v_mfma_f32_16x16x32_bf16 v[26:29], v[146:149], v[190:193], v[26:29]
	v_mfma_f32_16x16x32_bf16 v[10:13], v[154:157], v[190:193], v[10:13]
	v_mfma_f32_16x16x32_bf16 v[14:17], v[146:149], v[206:209], v[14:17]
	v_mfma_f32_16x16x32_bf16 v[2:5], v[154:157], v[206:209], v[2:5]
	v_mfma_f32_16x16x32_bf16 v[58:61], v[150:153], v[166:169], v[58:61]
	v_mfma_f32_16x16x32_bf16 v[30:33], v[158:161], v[166:169], v[30:33]
	v_mfma_f32_16x16x32_bf16 v[42:45], v[150:153], v[174:177], v[42:45]
	v_mfma_f32_16x16x32_bf16 v[6:9], v[158:161], v[174:177], v[6:9]
	v_mfma_f32_16x16x32_bf16 v[26:29], v[150:153], v[202:205], v[26:29]
	v_mfma_f32_16x16x32_bf16 v[10:13], v[158:161], v[202:205], v[10:13]
	v_mfma_f32_16x16x32_bf16 v[14:17], v[150:153], v[210:213], v[14:17]
	v_mfma_f32_16x16x32_bf16 v[2:5], v[158:161], v[210:213], v[2:5]
	s_setprio 0
	s_barrier
	s_add_i32 s31, s31, 2
	s_add_u32 s29, s29, 0x100
	s_addc_u32 s30, s30, 0
	s_cmp_gt_u32 s31, 29
	s_mov_b64 s[44:45], s[4:5]

;     __device__ __forceinline__ void operator()(f32x4 (&acc)[2][2][4][2], const Unit& u, int wr, int wc, int fr, int fq) const {
;     ...
;             const int tq = tok0 + 8 * fr; const int tA = tq < 0 ? 0 : (tq > TOK - 1 ? TOK - 1 : tq), tB = (tq + 7) > TOK - 1 ? TOK - 1 : (tq + 7);
;             const int bA = batch_of(tA), bB = batch_of(tB); const bool same = __all(bA == bB);
;             const float* bp0 = bias + 256 * u.pn + 32 * wc + 8 * fq;
;             f32x4 bvA[2][2]; float sq[8];
; #pragma unroll
;             for (int am = 0; am < 8; ++am) { int tok = tq + am; tok = tok < 0 ? 0 : (tok > TOK - 1 ? TOK - 1 : tok); sq[am] = LDG(float, ssq + tok); }
; #pragma unroll
;             for (int bj = 0; bj < 2; ++bj)
; #pragma unroll
;                 for (int n = 0; n < 2; ++n) bvA[bj][n] = LDG(f32x4, bp0 + (size_t)bA * (2 * DFF) + bj * HALF + 4 * n);
; #pragma unroll
;             for (int am = 0; am < 8; ++am) { const int ai = am >> 2, m = am & 3;
;                 const float rs = __builtin_amdgcn_rsqf(sq[am] * (1.f / DM) + EPS);
; #pragma unroll
;                 for (int bj = 0; bj < 2; ++bj)
; #pragma unroll
;                     for (int n = 0; n < 2; ++n) acc[ai][bj][m][n] = acc[ai][bj][m][n] * rs + bvA[bj][n];
;                 asm volatile("" : "+v"(acc[ai][0][m][0]), "+v"(acc[ai][0][m][1]), "+v"(acc[ai][1][m][0]), "+v"(acc[ai][1][m][1])); }
.LBB0_1302:
	s_mul_i32 s4, s26, 0xfc
	v_add_u32_e32 v203, s4, v197
	v_med3_i32 v130, v203, 0, v238
	v_add_u32_e32 v132, 0xffffe000, v130
	v_lshrrev_b32_e32 v132, 12, v132
	s_movk_i32 s4, 0x2000
	v_add_u32_e32 v214, 1, v203
	v_add_u32_e32 v207, 3, v203
	v_lshrrev_b32_e32 v131, 11, v130
	v_add_u32_e32 v132, 4, v132
	v_cmp_gt_i32_e32 vcc, s4, v203
	s_lshl_b32 s4, s92, 8
	v_lshlrev_b32_e32 v130, 2, v130
	v_med3_i32 v212, v214, 0, v238
	v_add_u32_e32 v208, 2, v203
	v_med3_i32 v210, v207, 0, v238
	v_cndmask_b32_e32 v192, v132, v131, vcc
	s_ashr_i32 s5, s4, 31
	v_mov_b32_e32 v132, v224
	v_lshlrev_b32_e32 v130, 2, v212
	v_med3_i32 v211, v208, 0, v238
	v_lshlrev_b32_e32 v133, 2, v210
	v_lshlrev_b32_e32 v131, 2, v211
	v_mov_b32_e32 v134, v228
	v_mov_b32_e32 v135, v231
	s_nop 0
	v_mov_b32_e32 v133, v233
	v_lshl_add_u64 v[190:191], s[4:5], 2, v[184:185]
	v_add_u32_e32 v206, 4, v203
	v_add_u32_e32 v202, 7, v203
	v_mad_u64_u32 v[130:131], s[4:5], v192, s15, v[190:191]
	v_med3_i32 v209, v206, 0, v238
	v_add_u32_e32 v205, 5, v203
	v_med3_i32 v193, v202, 0, v238
	v_mov_b64_e32 v[174:175], v[240:241]
	v_mov_b64_e32 v[176:177], v[242:243]
	v_mov_b64_e32 v[170:171], v[244:245]
	v_mov_b64_e32 v[172:173], v[246:247]
	v_mov_b64_e32 v[166:167], v[248:249]
	v_mov_b64_e32 v[168:169], v[250:251]
	v_mov_b64_e32 v[162:163], v[222:223]
	v_mov_b64_e32 v[164:165], v[236:237]
	v_lshlrev_b32_e32 v130, 2, v209
	v_med3_i32 v195, v205, 0, v238
	v_add_u32_e32 v204, 6, v203
	v_lshlrev_b32_e32 v136, 2, v193
	v_mov_b32_e32 v215, v234
	v_mov_b32_e32 v220, v253
	v_lshlrev_b32_e32 v130, 2, v195
	v_med3_i32 v194, v204, 0, v238
	v_mov_b32_e32 v217, v239
	v_lshlrev_b32_e32 v130, 2, v194
	v_mov_b32_e32 v219, v252
	v_min_i32_e32 v130, 0x9ff8, v203
	v_add_u32_e32 v131, 7, v130
	v_add_u32_e32 v130, 0xffffe007, v130
	v_lshrrev_b32_e32 v130, 12, v130
	s_movk_i32 s4, 0x1ff9
	v_ashrrev_i32_e32 v131, 11, v131
	v_add_u32_e32 v130, 4, v130
	v_cmp_gt_i32_e64 s[42:43], s4, v203
	s_waitcnt vmcnt(0)
	v_fmamk_f32 v133, v133, 0x3a000000, v226
	v_cndmask_b32_e64 v213, v130, v131, s[42:43]
	v_fmamk_f32 v130, v132, 0x3a000000, v226
	v_fmamk_f32 v131, v134, 0x3a000000, v226
	v_rsq_f32_e32 v130, v130
	v_rsq_f32_e32 v132, v131
	v_rsq_f32_e32 v218, v133
	v_fmamk_f32 v134, v135, 0x3a000000, v226
	v_pk_fma_f32 v[150:151], v[126:127], v[130:131], v[174:175] op_sel_hi:[1,0,1]
	v_pk_fma_f32 v[126:127], v[114:115], v[132:133], v[170:171] op_sel_hi:[1,0,1]
	v_rsq_f32_e32 v216, v134
	v_pk_fma_f32 v[142:143], v[122:123], v[130:131], v[170:171] op_sel_hi:[1,0,1]
	v_pk_fma_f32 v[152:153], v[128:129], v[130:131], v[176:177] op_sel_hi:[1,0,1]
	v_pk_fma_f32 v[128:129], v[116:117], v[132:133], v[172:173] op_sel_hi:[1,0,1]
	v_pk_fma_f32 v[144:145], v[124:125], v[130:131], v[172:173] op_sel_hi:[1,0,1]
	v_cmp_eq_u32_e64 s[44:45], v192, v213
	v_pk_fma_f32 v[160:161], v[108:109], v[130:131], v[168:169] op_sel_hi:[1,0,1]
	v_pk_fma_f32 v[158:159], v[106:107], v[130:131], v[166:167] op_sel_hi:[1,0,1]
	v_pk_fma_f32 v[122:123], v[62:63], v[216:217], v[162:163] op_sel_hi:[1,0,1]
	v_pk_fma_f32 v[124:125], v[64:65], v[216:217], v[164:165] op_sel_hi:[1,0,1]
	v_pk_fma_f32 v[114:115], v[78:79], v[218:219], v[166:167] op_sel_hi:[1,0,1]
	v_fmamk_f32 v78, v215, 0x3a000000, v226
	v_rsq_f32_e32 v78, v78
	v_pk_fma_f32 v[62:63], v[82:83], v[218:219], v[170:171] op_sel_hi:[1,0,1]
	v_pk_fma_f32 v[82:83], v[66:67], v[218:219], v[162:163] op_sel_hi:[1,0,1]
	v_pk_fma_f32 v[116:117], v[80:81], v[218:219], v[168:169] op_sel_hi:[1,0,1]
	v_pk_fma_f32 v[66:67], v[58:59], v[78:79], v[166:167] op_sel_hi:[1,0,1]
	v_fmamk_f32 v58, v217, 0x3a000000, v226
	v_rsq_f32_e32 v80, v58
	v_pk_fma_f32 v[58:59], v[30:31], v[78:79], v[162:163] op_sel_hi:[1,0,1]
	v_pk_fma_f32 v[64:65], v[84:85], v[218:219], v[172:173] op_sel_hi:[1,0,1]
	v_pk_fma_f32 v[84:85], v[68:69], v[218:219], v[164:165] op_sel_hi:[1,0,1]
	v_pk_fma_f32 v[30:31], v[50:51], v[80:81], v[170:171] op_sel_hi:[1,0,1]
	v_pk_fma_f32 v[50:51], v[42:43], v[80:81], v[166:167] op_sel_hi:[1,0,1]
	v_fmamk_f32 v42, v219, 0x3a000000, v226
	v_pk_fma_f32 v[56:57], v[56:57], v[78:79], v[176:177] op_sel_hi:[1,0,1]
	v_pk_fma_f32 v[54:55], v[54:55], v[78:79], v[174:175] op_sel_hi:[1,0,1]
	v_pk_fma_f32 v[48:49], v[48:49], v[78:79], v[172:173] op_sel_hi:[1,0,1]
	v_pk_fma_f32 v[46:47], v[46:47], v[78:79], v[170:171] op_sel_hi:[1,0,1]
	v_pk_fma_f32 v[68:69], v[60:61], v[78:79], v[168:169] op_sel_hi:[1,0,1]
	v_pk_fma_f32 v[60:61], v[32:33], v[78:79], v[164:165] op_sel_hi:[1,0,1]
	v_rsq_f32_e32 v78, v42
	v_pk_fma_f32 v[42:43], v[6:7], v[80:81], v[162:163] op_sel_hi:[1,0,1]
	v_pk_fma_f32 v[40:41], v[40:41], v[80:81], v[176:177] op_sel_hi:[1,0,1]
	v_pk_fma_f32 v[38:39], v[38:39], v[80:81], v[174:175] op_sel_hi:[1,0,1]
	v_pk_fma_f32 v[6:7], v[34:35], v[78:79], v[170:171] op_sel_hi:[1,0,1]
	v_pk_fma_f32 v[34:35], v[26:27], v[78:79], v[166:167] op_sel_hi:[1,0,1]
	v_fmamk_f32 v26, v220, 0x3a000000, v226
	v_pk_fma_f32 v[32:33], v[52:53], v[80:81], v[172:173] op_sel_hi:[1,0,1]
	v_pk_fma_f32 v[52:53], v[44:45], v[80:81], v[168:169] op_sel_hi:[1,0,1]
	v_pk_fma_f32 v[44:45], v[8:9], v[80:81], v[164:165] op_sel_hi:[1,0,1]
	v_rsq_f32_e32 v80, v26
	v_pk_fma_f32 v[156:157], v[100:101], v[130:131], v[164:165] op_sel_hi:[1,0,1]
	v_pk_fma_f32 v[154:155], v[98:99], v[130:131], v[162:163] op_sel_hi:[1,0,1]
	v_pk_fma_f32 v[136:137], v[120:121], v[132:133], v[176:177] op_sel_hi:[1,0,1]
	v_pk_fma_f32 v[134:135], v[118:119], v[132:133], v[174:175] op_sel_hi:[1,0,1]
	v_pk_fma_f32 v[148:149], v[96:97], v[132:133], v[168:169] op_sel_hi:[1,0,1]
	v_pk_fma_f32 v[146:147], v[94:95], v[132:133], v[166:167] op_sel_hi:[1,0,1]
;     __device__ __forceinline__ void operator()(f32x4 (&acc)[2][2][4][2], const Unit& u, int wr, int wc, int fr, int fq) const {
;     ...
; #pragma unroll
;                     for (int n = 0; n < 2; ++n) acc[ai][bj][m][n] = acc[ai][bj][m][n] * rs + bvA[bj][n];
;                 asm volatile("" : "+v"(acc[ai][0][m][0]), "+v"(acc[ai][0][m][1]), "+v"(acc[ai][1][m][0]), "+v"(acc[ai][1][m][1])); }
;             if (!same) {
;                 asm volatile("" ::: "memory");
;                 f32x4 dv[2][2];
; #pragma unroll
;                 for (int bj = 0; bj < 2; ++bj)
; #pragma unroll
;                     for (int n = 0; n < 2; ++n) dv[bj][n] = LDG(f32x4, bp0 + (size_t)bB * (2 * DFF) + bj * HALF + 4 * n) - bvA[bj][n];
	v_pk_fma_f32 v[140:141], v[88:89], v[132:133], v[164:165] op_sel_hi:[1,0,1]
	v_pk_fma_f32 v[138:139], v[86:87], v[132:133], v[162:163] op_sel_hi:[1,0,1]
	v_pk_fma_f32 v[120:121], v[112:113], v[216:217], v[176:177] op_sel_hi:[1,0,1]
	v_pk_fma_f32 v[118:119], v[110:111], v[216:217], v[174:175] op_sel_hi:[1,0,1]
	v_pk_fma_f32 v[96:97], v[104:105], v[216:217], v[172:173] op_sel_hi:[1,0,1]
	v_pk_fma_f32 v[94:95], v[102:103], v[216:217], v[170:171] op_sel_hi:[1,0,1]
	v_pk_fma_f32 v[132:133], v[72:73], v[216:217], v[168:169] op_sel_hi:[1,0,1]
	v_pk_fma_f32 v[130:131], v[70:71], v[216:217], v[166:167] op_sel_hi:[1,0,1]
	v_pk_fma_f32 v[72:73], v[92:93], v[218:219], v[176:177] op_sel_hi:[1,0,1]
	v_pk_fma_f32 v[70:71], v[90:91], v[218:219], v[174:175] op_sel_hi:[1,0,1]
	v_pk_fma_f32 v[20:21], v[20:21], v[78:79], v[176:177] op_sel_hi:[1,0,1]
	v_pk_fma_f32 v[18:19], v[18:19], v[78:79], v[174:175] op_sel_hi:[1,0,1]
	v_pk_fma_f32 v[8:9], v[36:37], v[78:79], v[172:173] op_sel_hi:[1,0,1]
	v_pk_fma_f32 v[36:37], v[28:29], v[78:79], v[168:169] op_sel_hi:[1,0,1]
	v_pk_fma_f32 v[28:29], v[12:13], v[78:79], v[164:165] op_sel_hi:[1,0,1]
	v_pk_fma_f32 v[26:27], v[10:11], v[78:79], v[162:163] op_sel_hi:[1,0,1]
	v_pk_fma_f32 v[24:25], v[24:25], v[80:81], v[176:177] op_sel_hi:[1,0,1]
	v_pk_fma_f32 v[22:23], v[22:23], v[80:81], v[174:175] op_sel_hi:[1,0,1]
	v_pk_fma_f32 v[12:13], v[76:77], v[80:81], v[172:173] op_sel_hi:[1,0,1]
	v_pk_fma_f32 v[10:11], v[74:75], v[80:81], v[170:171] op_sel_hi:[1,0,1]
	v_pk_fma_f32 v[16:17], v[16:17], v[80:81], v[168:169] op_sel_hi:[1,0,1]
	v_pk_fma_f32 v[14:15], v[14:15], v[80:81], v[166:167] op_sel_hi:[1,0,1]
	v_pk_fma_f32 v[4:5], v[4:5], v[80:81], v[164:165] op_sel_hi:[1,0,1]
	v_pk_fma_f32 v[2:3], v[2:3], v[80:81], v[162:163] op_sel_hi:[1,0,1]
	s_cmp_eq_u64 s[44:45], exec
	s_cbranch_scc1 .LBB0_1304
	v_mul_hi_i32_i24_e32 v75, 0xac00, v213
	v_mul_i32_i24_e32 v74, 0xac00, v213
	v_lshl_add_u64 v[90:91], v[190:191], 0, v[74:75]
	global_load_dwordx4 v[74:77], v[90:91], off offset:16
	global_load_dwordx4 v[78:81], v[90:91], off
	global_load_dwordx4 v[86:89], v[90:91], off offset:528
	s_nop 0
	global_load_dwordx4 v[90:93], v[90:91], off offset:512
	v_add_u32_e32 v99, 0xffffe000, v212
	s_movk_i32 s4, 0x1fff
	v_lshrrev_b32_e32 v99, 12, v99
	v_cmp_gt_i32_e64 s[44:45], s4, v203
	v_lshrrev_b32_e32 v98, 11, v212
	v_add_u32_e32 v99, 4, v99
	v_cndmask_b32_e64 v98, v99, v98, s[44:45]
	v_cmp_eq_u32_e64 s[44:45], v98, v192
	s_movk_i32 s4, 0x1ffe
	s_waitcnt vmcnt(3)
	v_sub_f32_e32 v75, v75, v171
	s_waitcnt vmcnt(2)
	v_sub_f32_e32 v79, v79, v175
	v_sub_f32_e32 v78, v78, v174
	v_sub_f32_e32 v81, v81, v177
	v_sub_f32_e32 v80, v80, v176
	v_sub_f32_e32 v74, v74, v170
	v_sub_f32_e32 v77, v77, v173
	v_sub_f32_e32 v76, v76, v172
	s_waitcnt vmcnt(0)
;     __device__ __forceinline__ void operator()(f32x4 (&acc)[2][2][4][2], const Unit& u, int wr, int wc, int fr, int fq) const {
;     ...
;                     for (int n = 0; n < 2; ++n) dv[bj][n] = LDG(f32x4, bp0 + (size_t)bB * (2 * DFF) + bj * HALF + 4 * n) - bvA[bj][n];
; #pragma unroll
;                 for (int am = 0; am < 8; ++am) { const int ai = am >> 2, m = am & 3; int tok = tq + am; tok = tok < 0 ? 0 : (tok > TOK - 1 ? TOK - 1 : tok);
;                     const float mB = (batch_of(tok) == bA) ? 0.f : 1.f;
; #pragma unroll
;                     for (int bj = 0; bj < 2; ++bj)
; #pragma unroll
;                         for (int n = 0; n < 2; ++n) acc[ai][bj][m][n] += dv[bj][n] * mB; } } }
	v_sub_f32_e32 v91, v91, v167
	v_sub_f32_e32 v90, v90, v166
	v_sub_f32_e32 v93, v93, v169
	v_sub_f32_e32 v92, v92, v168
	v_sub_f32_e32 v87, v87, v163
	v_sub_f32_e32 v86, v86, v162
	v_sub_f32_e32 v89, v89, v165
	v_sub_f32_e32 v88, v88, v164
	v_cndmask_b32_e64 v98, 1.0, 0, s[44:45]
	v_pk_fma_f32 v[136:137], v[98:99], v[80:81], v[136:137] op_sel_hi:[0,1,1]
	v_pk_fma_f32 v[134:135], v[98:99], v[78:79], v[134:135] op_sel_hi:[0,1,1]
	v_pk_fma_f32 v[128:129], v[98:99], v[76:77], v[128:129] op_sel_hi:[0,1,1]
	v_pk_fma_f32 v[126:127], v[98:99], v[74:75], v[126:127] op_sel_hi:[0,1,1]
	v_pk_fma_f32 v[148:149], v[98:99], v[92:93], v[148:149] op_sel_hi:[0,1,1]
	v_pk_fma_f32 v[146:147], v[98:99], v[90:91], v[146:147] op_sel_hi:[0,1,1]
	v_pk_fma_f32 v[140:141], v[98:99], v[88:89], v[140:141] op_sel_hi:[0,1,1]
	v_pk_fma_f32 v[138:139], v[98:99], v[86:87], v[138:139] op_sel_hi:[0,1,1]
	v_add_u32_e32 v99, 0xffffe000, v211
	v_lshrrev_b32_e32 v99, 12, v99
	v_cmp_gt_i32_e64 s[44:45], s4, v203
	v_lshrrev_b32_e32 v98, 11, v211
	v_add_u32_e32 v99, 4, v99
	v_cndmask_b32_e64 v98, v99, v98, s[44:45]
	v_cmp_eq_u32_e64 s[44:45], v98, v192
	s_movk_i32 s4, 0x1ffd
	v_pk_fma_f32 v[152:153], v[80:81], 0, v[152:153] op_sel_hi:[1,0,1]
	v_cndmask_b32_e64 v98, 1.0, 0, s[44:45]
	v_pk_fma_f32 v[120:121], v[98:99], v[80:81], v[120:121] op_sel_hi:[0,1,1]
	v_pk_fma_f32 v[118:119], v[98:99], v[78:79], v[118:119] op_sel_hi:[0,1,1]
	v_pk_fma_f32 v[96:97], v[98:99], v[76:77], v[96:97] op_sel_hi:[0,1,1]
	v_pk_fma_f32 v[94:95], v[98:99], v[74:75], v[94:95] op_sel_hi:[0,1,1]
	v_pk_fma_f32 v[132:133], v[98:99], v[92:93], v[132:133] op_sel_hi:[0,1,1]
	v_pk_fma_f32 v[130:131], v[98:99], v[90:91], v[130:131] op_sel_hi:[0,1,1]
	v_pk_fma_f32 v[124:125], v[98:99], v[88:89], v[124:125] op_sel_hi:[0,1,1]
	v_pk_fma_f32 v[122:123], v[98:99], v[86:87], v[122:123] op_sel_hi:[0,1,1]
	v_add_u32_e32 v99, 0xffffe000, v210
	v_lshrrev_b32_e32 v99, 12, v99
	v_cmp_gt_i32_e64 s[44:45], s4, v203
	v_lshrrev_b32_e32 v98, 11, v210
	v_add_u32_e32 v99, 4, v99
	v_cndmask_b32_e64 v98, v99, v98, s[44:45]
	v_cmp_eq_u32_e64 s[44:45], v98, v192
	s_movk_i32 s4, 0x1ffc
	v_pk_fma_f32 v[150:151], v[78:79], 0, v[150:151] op_sel_hi:[1,0,1]
	v_cndmask_b32_e64 v98, 1.0, 0, s[44:45]
	v_pk_fma_f32 v[72:73], v[98:99], v[80:81], v[72:73] op_sel_hi:[0,1,1]
	v_pk_fma_f32 v[70:71], v[98:99], v[78:79], v[70:71] op_sel_hi:[0,1,1]
	v_pk_fma_f32 v[64:65], v[98:99], v[76:77], v[64:65] op_sel_hi:[0,1,1]
	v_pk_fma_f32 v[62:63], v[98:99], v[74:75], v[62:63] op_sel_hi:[0,1,1]
	v_pk_fma_f32 v[116:117], v[98:99], v[92:93], v[116:117] op_sel_hi:[0,1,1]
	v_pk_fma_f32 v[114:115], v[98:99], v[90:91], v[114:115] op_sel_hi:[0,1,1]
	v_pk_fma_f32 v[84:85], v[98:99], v[88:89], v[84:85] op_sel_hi:[0,1,1]
	v_pk_fma_f32 v[82:83], v[98:99], v[86:87], v[82:83] op_sel_hi:[0,1,1]
	v_add_u32_e32 v99, 0xffffe000, v209
	v_lshrrev_b32_e32 v99, 12, v99
	v_cmp_gt_i32_e64 s[44:45], s4, v203
	v_lshrrev_b32_e32 v98, 11, v209
	v_add_u32_e32 v99, 4, v99
	v_cndmask_b32_e64 v98, v99, v98, s[44:45]
	v_cmp_eq_u32_e64 s[44:45], v98, v192
	s_movk_i32 s4, 0x1ffb
	v_pk_fma_f32 v[144:145], v[76:77], 0, v[144:145] op_sel_hi:[1,0,1]
	v_cndmask_b32_e64 v98, 1.0, 0, s[44:45]
	v_pk_fma_f32 v[56:57], v[98:99], v[80:81], v[56:57] op_sel_hi:[0,1,1]
	v_pk_fma_f32 v[54:55], v[98:99], v[78:79], v[54:55] op_sel_hi:[0,1,1]
	v_pk_fma_f32 v[48:49], v[98:99], v[76:77], v[48:49] op_sel_hi:[0,1,1]
	v_pk_fma_f32 v[46:47], v[98:99], v[74:75], v[46:47] op_sel_hi:[0,1,1]
	v_pk_fma_f32 v[68:69], v[98:99], v[92:93], v[68:69] op_sel_hi:[0,1,1]
	v_pk_fma_f32 v[66:67], v[98:99], v[90:91], v[66:67] op_sel_hi:[0,1,1]
	v_pk_fma_f32 v[60:61], v[98:99], v[88:89], v[60:61] op_sel_hi:[0,1,1]
	v_pk_fma_f32 v[58:59], v[98:99], v[86:87], v[58:59] op_sel_hi:[0,1,1]
	v_add_u32_e32 v99, 0xffffe000, v195
	v_lshrrev_b32_e32 v99, 12, v99
	v_cmp_gt_i32_e64 s[44:45], s4, v203
	v_lshrrev_b32_e32 v98, 11, v195
	v_add_u32_e32 v99, 4, v99
	v_cndmask_b32_e64 v98, v99, v98, s[44:45]
	v_cmp_eq_u32_e64 s[44:45], v98, v192
	s_movk_i32 s4, 0x1ffa
	v_pk_fma_f32 v[142:143], v[74:75], 0, v[142:143] op_sel_hi:[1,0,1]
	v_cndmask_b32_e64 v98, 1.0, 0, s[44:45]
	v_pk_fma_f32 v[40:41], v[98:99], v[80:81], v[40:41] op_sel_hi:[0,1,1]
	v_pk_fma_f32 v[38:39], v[98:99], v[78:79], v[38:39] op_sel_hi:[0,1,1]
	v_pk_fma_f32 v[32:33], v[98:99], v[76:77], v[32:33] op_sel_hi:[0,1,1]
	v_pk_fma_f32 v[30:31], v[98:99], v[74:75], v[30:31] op_sel_hi:[0,1,1]
	v_pk_fma_f32 v[52:53], v[98:99], v[92:93], v[52:53] op_sel_hi:[0,1,1]
	v_pk_fma_f32 v[50:51], v[98:99], v[90:91], v[50:51] op_sel_hi:[0,1,1]
	v_pk_fma_f32 v[44:45], v[98:99], v[88:89], v[44:45] op_sel_hi:[0,1,1]
	v_pk_fma_f32 v[42:43], v[98:99], v[86:87], v[42:43] op_sel_hi:[0,1,1]
	v_add_u32_e32 v99, 0xffffe000, v194
	v_lshrrev_b32_e32 v99, 12, v99
	v_cmp_gt_i32_e64 s[44:45], s4, v203
	v_lshrrev_b32_e32 v98, 11, v194
	v_add_u32_e32 v99, 4, v99
	v_cndmask_b32_e64 v98, v99, v98, s[44:45]
	v_cmp_eq_u32_e64 s[44:45], v98, v192
	v_pk_fma_f32 v[160:161], v[92:93], 0, v[160:161] op_sel_hi:[1,0,1]
	v_pk_fma_f32 v[158:159], v[90:91], 0, v[158:159] op_sel_hi:[1,0,1]
	v_cndmask_b32_e64 v98, 1.0, 0, s[44:45]
	v_pk_fma_f32 v[20:21], v[98:99], v[80:81], v[20:21] op_sel_hi:[0,1,1]
	v_pk_fma_f32 v[18:19], v[98:99], v[78:79], v[18:19] op_sel_hi:[0,1,1]
	v_pk_fma_f32 v[8:9], v[98:99], v[76:77], v[8:9] op_sel_hi:[0,1,1]
	v_pk_fma_f32 v[6:7], v[98:99], v[74:75], v[6:7] op_sel_hi:[0,1,1]
	v_pk_fma_f32 v[36:37], v[98:99], v[92:93], v[36:37] op_sel_hi:[0,1,1]
	v_pk_fma_f32 v[34:35], v[98:99], v[90:91], v[34:35] op_sel_hi:[0,1,1]
	v_pk_fma_f32 v[28:29], v[98:99], v[88:89], v[28:29] op_sel_hi:[0,1,1]
	v_pk_fma_f32 v[26:27], v[98:99], v[86:87], v[26:27] op_sel_hi:[0,1,1]
	v_add_u32_e32 v99, 0xffffe000, v193
	v_lshrrev_b32_e32 v99, 12, v99
	v_lshrrev_b32_e32 v98, 11, v193
	v_add_u32_e32 v99, 4, v99
	v_cndmask_b32_e64 v98, v99, v98, s[42:43]
	v_cmp_eq_u32_e64 s[42:43], v98, v192
	v_pk_fma_f32 v[156:157], v[88:89], 0, v[156:157] op_sel_hi:[1,0,1]
	v_pk_fma_f32 v[154:155], v[86:87], 0, v[154:155] op_sel_hi:[1,0,1]
	v_cndmask_b32_e64 v98, 1.0, 0, s[42:43]
	v_pk_fma_f32 v[24:25], v[98:99], v[80:81], v[24:25] op_sel_hi:[0,1,1]
	v_pk_fma_f32 v[22:23], v[98:99], v[78:79], v[22:23] op_sel_hi:[0,1,1]
	v_pk_fma_f32 v[12:13], v[98:99], v[76:77], v[12:13] op_sel_hi:[0,1,1]
	v_pk_fma_f32 v[10:11], v[98:99], v[74:75], v[10:11] op_sel_hi:[0,1,1]
	v_pk_fma_f32 v[16:17], v[98:99], v[92:93], v[16:17] op_sel_hi:[0,1,1]
	v_pk_fma_f32 v[14:15], v[98:99], v[90:91], v[14:15] op_sel_hi:[0,1,1]
	v_pk_fma_f32 v[4:5], v[98:99], v[88:89], v[4:5] op_sel_hi:[0,1,1]
	v_pk_fma_f32 v[2:3], v[98:99], v[86:87], v[2:3] op_sel_hi:[0,1,1]
